# v8 plus: grid-barrier acquire invalidate (buffer_inv sc1) issued before the spin / while the top-level atomic is in flight
# speedup vs baseline: 1.0402x; 1.0402x over previous
; __device__ __forceinline__ unsigned xb_ld(unsigned* p)              { return __hip_atomic_load(p, __ATOMIC_RELAXED, __HIP_MEMORY_SCOPE_AGENT); }
; __device__ __forceinline__ unsigned xb_add(unsigned* p, unsigned v) { return __hip_atomic_fetch_add(p, v, __ATOMIC_RELAXED, __HIP_MEMORY_SCOPE_AGENT); }
; #define XB_SPIN(cond, bar) do { unsigned _sp = 0; while (cond) { __builtin_amdgcn_s_sleep(1); \
;     if ((++_sp & 255u) == 0u) { if (xb_ld(&(bar)[XB_TMO])) break; if (_sp > XB_SPIN_CAP) { atomicAdd(&(bar)[XB_TMO], 1u); break; } } } } while (0)
; __device__ __forceinline__ void xcd_barrier(const XcdBarrier& b) {
;     ...
;         const unsigned old = xb_add(&bar[XB_XSUB(b.x)], 1u);
;         const unsigned gen = old / nloc;
;         if (old + 1u == (gen + 1u) * nloc) {
;             __builtin_amdgcn_fence(__ATOMIC_RELEASE, "agent");
;             asm volatile("s_waitcnt vmcnt(0)" ::: "memory");
;             const unsigned og = xb_add(&bar[XB_TOP], 1u);
;             const unsigned tg = og / nx;
;             if (og + 1u == (tg + 1u) * nx) xb_add(&bar[XB_TOPGEN], 1u);
;             else XB_SPIN(xb_ld(&bar[XB_TOPGEN]) == tg, bar);
;             __builtin_amdgcn_fence(__ATOMIC_ACQUIRE, "agent");
;             xb_add(&bar[XB_XGEN(b.x)], 1u);
;             asm volatile("s_waitcnt vmcnt(0)" ::: "memory");
;         } else {
;             XB_SPIN(xb_ld(&bar[XB_XGEN(b.x)]) == gen, bar);
.LBB0_70:
	s_or_b64 exec, exec, s[12:13]
	v_cvt_f32_u32_e32 v4, v2
	s_waitcnt vmcnt(0)
	v_readfirstlane_b32 s6, v3
	v_sub_u32_e32 v3, 0, v2
	v_rcp_iflag_f32_e32 v4, v4
	v_add_u32_e32 v5, s6, v1
	v_mul_f32_e32 v4, 0x4f7ffffe, v4
	v_cvt_u32_f32_e32 v4, v4
	v_mul_lo_u32 v1, v3, v4
	v_mul_hi_u32 v1, v4, v1
	v_add_u32_e32 v1, v4, v1
	v_mul_hi_u32 v1, v5, v1
	v_mul_lo_u32 v3, v1, v2
	v_sub_u32_e32 v3, v5, v3
	v_add_u32_e32 v4, 1, v1
	v_cmp_ge_u32_e32 vcc, v3, v2
	s_nop 1
	v_cndmask_b32_e32 v1, v1, v4, vcc
	v_sub_u32_e32 v4, v3, v2
	v_cndmask_b32_e32 v3, v3, v4, vcc
	v_add_u32_e32 v4, 1, v1
	v_cmp_ge_u32_e32 vcc, v3, v2
	v_add_u32_e32 v3, 1, v5
	s_nop 0
	v_cndmask_b32_e32 v1, v1, v4, vcc
	v_mul_lo_u32 v4, v2, v1
	v_add_u32_e32 v2, v4, v2
	v_cmp_ne_u32_e32 vcc, v3, v2
	s_and_saveexec_b64 s[6:7], vcc
	s_xor_b64 s[12:13], exec, s[6:7]
	s_cbranch_execz .LBB0_84
	s_waitcnt lgkmcnt(0)
	v_mov_b32_e32 v0, 0x2000
	buffer_inv sc1
	global_load_dword v0, v0, s[10:11] offset:1024 sc1
	s_add_u32 s18, s10, 0x2400
	s_addc_u32 s19, s11, 0
	s_waitcnt vmcnt(0)
	v_cmp_eq_u32_e32 vcc, v0, v1
	s_and_saveexec_b64 s[14:15], vcc
	s_cbranch_execz .LBB0_83
	s_add_u32 s16, s62, 0x1de00200
	s_addc_u32 s17, s63, 0
	s_mov_b32 s6, 1
	s_mov_b64 s[20:21], 0
	v_mov_b32_e32 v0, 0
	s_branch .LBB0_74

; __device__ __forceinline__ unsigned xb_ld(unsigned* p)              { return __hip_atomic_load(p, __ATOMIC_RELAXED, __HIP_MEMORY_SCOPE_AGENT); }
; #define XB_SPIN(cond, bar) do { unsigned _sp = 0; while (cond) { __builtin_amdgcn_s_sleep(1); \
;     if ((++_sp & 255u) == 0u) { if (xb_ld(&(bar)[XB_TMO])) break; if (_sp > XB_SPIN_CAP) { atomicAdd(&(bar)[XB_TMO], 1u); break; } } } } while (0)
; __device__ __forceinline__ void xcd_barrier(const XcdBarrier& b) {
;     ...
;             XB_SPIN(xb_ld(&bar[XB_XGEN(b.x)]) == gen, bar);
;             __builtin_amdgcn_fence(__ATOMIC_ACQUIRE, "agent");
;             asm volatile("s_waitcnt vmcnt(0)" ::: "memory");
.LBB0_83:
	s_or_b64 exec, exec, s[14:15]
	s_waitcnt vmcnt(0)
	s_waitcnt vmcnt(0)

; __device__ __forceinline__ unsigned xb_ld(unsigned* p)              { return __hip_atomic_load(p, __ATOMIC_RELAXED, __HIP_MEMORY_SCOPE_AGENT); }
; __device__ __forceinline__ unsigned xb_add(unsigned* p, unsigned v) { return __hip_atomic_fetch_add(p, v, __ATOMIC_RELAXED, __HIP_MEMORY_SCOPE_AGENT); }
; #define XB_SPIN(cond, bar) do { unsigned _sp = 0; while (cond) { __builtin_amdgcn_s_sleep(1); \
;     if ((++_sp & 255u) == 0u) { if (xb_ld(&(bar)[XB_TMO])) break; if (_sp > XB_SPIN_CAP) { atomicAdd(&(bar)[XB_TMO], 1u); break; } } } } while (0)
; __device__ __forceinline__ void xcd_barrier(const XcdBarrier& b) {
;     ...
;         if (old + 1u == (gen + 1u) * nloc) {
;             __builtin_amdgcn_fence(__ATOMIC_RELEASE, "agent");
;             asm volatile("s_waitcnt vmcnt(0)" ::: "memory");
;             const unsigned og = xb_add(&bar[XB_TOP], 1u);
;             const unsigned tg = og / nx;
;             if (og + 1u == (tg + 1u) * nx) xb_add(&bar[XB_TOPGEN], 1u);
;             else XB_SPIN(xb_ld(&bar[XB_TOPGEN]) == tg, bar);
.LBB0_87:
	s_or_b64 exec, exec, s[12:13]
	buffer_inv sc1
	v_cvt_f32_u32_e32 v3, v0
	s_waitcnt vmcnt(0)
	v_readfirstlane_b32 s6, v2
	s_add_u32 s14, s62, 0x1de03500
	s_addc_u32 s15, s63, 0
	v_rcp_iflag_f32_e32 v3, v3
	v_add_u32_e32 v1, s6, v1
	v_add_u32_e32 v4, 1, v1
	s_mov_b64 s[6:7], -1
	v_mul_f32_e32 v2, 0x4f7ffffe, v3
	v_cvt_u32_f32_e32 v2, v2
	v_sub_u32_e32 v3, 0, v0
	v_mul_lo_u32 v3, v3, v2
	v_mul_hi_u32 v3, v2, v3
	v_add_u32_e32 v2, v2, v3
	v_mul_hi_u32 v2, v1, v2
	v_mul_lo_u32 v3, v2, v0
	v_sub_u32_e32 v1, v1, v3
	v_add_u32_e32 v5, 1, v2
	v_cmp_ge_u32_e32 vcc, v1, v0
	v_sub_u32_e32 v3, v1, v0
	s_nop 0
	v_cndmask_b32_e32 v2, v2, v5, vcc
	v_cndmask_b32_e32 v1, v1, v3, vcc
	v_add_u32_e32 v3, 1, v2
	v_cmp_ge_u32_e32 vcc, v1, v0
	s_nop 1
	v_cndmask_b32_e32 v2, v2, v3, vcc
	v_mul_lo_u32 v1, v0, v2
	v_add_u32_e32 v0, v1, v0
	v_cmp_ne_u32_e32 vcc, v4, v0
	v_mov_b64_e32 v[0:1], s[14:15]
	s_and_saveexec_b64 s[12:13], vcc
	s_cbranch_execz .LBB0_99
	v_mov_b32_e32 v0, 0
	global_load_dword v1, v0, s[14:15] sc1
	s_mov_b64 s[6:7], 0
	s_waitcnt vmcnt(0)
	v_cmp_eq_u32_e32 vcc, v1, v2
	s_and_saveexec_b64 s[18:19], vcc
	s_cbranch_execz .LBB0_98
	s_add_u32 s16, s62, 0x1de00200
	s_addc_u32 s17, s63, 0
	s_mov_b32 s28, 1
	s_mov_b64 s[20:21], 0
	s_branch .LBB0_91

; __device__ __forceinline__ unsigned xb_add(unsigned* p, unsigned v) { return __hip_atomic_fetch_add(p, v, __ATOMIC_RELAXED, __HIP_MEMORY_SCOPE_AGENT); }
; __device__ __forceinline__ void xcd_barrier(const XcdBarrier& b) {
;     ...
;             __builtin_amdgcn_fence(__ATOMIC_ACQUIRE, "agent");
;             xb_add(&bar[XB_XGEN(b.x)], 1u);
;             asm volatile("s_waitcnt vmcnt(0)" ::: "memory");
.LBB0_101:
	s_or_b64 exec, exec, s[12:13]
	s_mov_b64 s[6:7], exec
	v_mbcnt_lo_u32_b32 v0, s6, 0
	v_mbcnt_hi_u32_b32 v0, s7, v0
	v_cmp_eq_u32_e32 vcc, 0, v0
	s_waitcnt vmcnt(0)
	s_and_saveexec_b64 s[12:13], vcc
	s_cbranch_execz .LBB0_103
	s_bcnt1_i32_b64 s6, s[6:7]
	v_mov_b32_e32 v0, 0x2000
	v_mov_b32_e32 v1, s6
	global_atomic_add v0, v1, s[10:11] offset:1024

; __device__ __forceinline__ unsigned xb_ld(unsigned* p)              { return __hip_atomic_load(p, __ATOMIC_RELAXED, __HIP_MEMORY_SCOPE_AGENT); }
; __device__ __forceinline__ unsigned xb_add(unsigned* p, unsigned v) { return __hip_atomic_fetch_add(p, v, __ATOMIC_RELAXED, __HIP_MEMORY_SCOPE_AGENT); }
; #define XB_SPIN(cond, bar) do { unsigned _sp = 0; while (cond) { __builtin_amdgcn_s_sleep(1); \
;     if ((++_sp & 255u) == 0u) { if (xb_ld(&(bar)[XB_TMO])) break; if (_sp > XB_SPIN_CAP) { atomicAdd(&(bar)[XB_TMO], 1u); break; } } } } while (0)
; __device__ __forceinline__ void xcd_barrier(const XcdBarrier& b) {
;     ...
;         const unsigned old = xb_add(&bar[XB_XSUB(b.x)], 1u);
;         const unsigned gen = old / nloc;
;         if (old + 1u == (gen + 1u) * nloc) {
;             __builtin_amdgcn_fence(__ATOMIC_RELEASE, "agent");
;             asm volatile("s_waitcnt vmcnt(0)" ::: "memory");
;             const unsigned og = xb_add(&bar[XB_TOP], 1u);
;             const unsigned tg = og / nx;
;             if (og + 1u == (tg + 1u) * nx) xb_add(&bar[XB_TOPGEN], 1u);
;             else XB_SPIN(xb_ld(&bar[XB_TOPGEN]) == tg, bar);
;             __builtin_amdgcn_fence(__ATOMIC_ACQUIRE, "agent");
;             xb_add(&bar[XB_XGEN(b.x)], 1u);
;             asm volatile("s_waitcnt vmcnt(0)" ::: "memory");
;         } else {
;             XB_SPIN(xb_ld(&bar[XB_XGEN(b.x)]) == gen, bar);
.LBB0_459:
	s_or_b64 exec, exec, s[10:11]
	v_cvt_f32_u32_e32 v4, v2
	s_waitcnt vmcnt(0)
	v_readfirstlane_b32 s8, v3
	v_sub_u32_e32 v3, 0, v2
	v_rcp_iflag_f32_e32 v4, v4
	v_add_u32_e32 v5, s8, v1
	v_mul_f32_e32 v4, 0x4f7ffffe, v4
	v_cvt_u32_f32_e32 v4, v4
	v_mul_lo_u32 v1, v3, v4
	v_mul_hi_u32 v1, v4, v1
	v_add_u32_e32 v1, v4, v1
	v_mul_hi_u32 v1, v5, v1
	v_mul_lo_u32 v3, v1, v2
	v_sub_u32_e32 v3, v5, v3
	v_add_u32_e32 v4, 1, v1
	v_cmp_ge_u32_e32 vcc, v3, v2
	s_nop 1
	v_cndmask_b32_e32 v1, v1, v4, vcc
	v_sub_u32_e32 v4, v3, v2
	v_cndmask_b32_e32 v3, v3, v4, vcc
	v_add_u32_e32 v4, 1, v1
	v_cmp_ge_u32_e32 vcc, v3, v2
	v_add_u32_e32 v3, 1, v5
	s_nop 0
	v_cndmask_b32_e32 v1, v1, v4, vcc
	v_mul_lo_u32 v4, v2, v1
	v_add_u32_e32 v2, v4, v2
	v_cmp_ne_u32_e32 vcc, v3, v2
	s_and_saveexec_b64 s[8:9], vcc
	s_xor_b64 s[8:9], exec, s[8:9]
	s_cbranch_execz .LBB0_473
	s_waitcnt lgkmcnt(0)
	v_mov_b32_e32 v0, 0x2000
	buffer_inv sc1
	global_load_dword v0, v0, s[6:7] offset:1024 sc1
	s_add_u32 s14, s6, 0x2400
	s_addc_u32 s15, s7, 0
	s_waitcnt vmcnt(0)
	v_cmp_eq_u32_e32 vcc, v0, v1
	s_and_saveexec_b64 s[10:11], vcc
	s_cbranch_execz .LBB0_472
	s_add_u32 s12, s62, 0x1de00200
	s_addc_u32 s13, s63, 0
	s_mov_b32 s26, 1
	s_mov_b64 s[16:17], 0
	v_mov_b32_e32 v0, 0
	s_branch .LBB0_463

; __device__ __forceinline__ unsigned xb_ld(unsigned* p)              { return __hip_atomic_load(p, __ATOMIC_RELAXED, __HIP_MEMORY_SCOPE_AGENT); }
; #define XB_SPIN(cond, bar) do { unsigned _sp = 0; while (cond) { __builtin_amdgcn_s_sleep(1); \
;     if ((++_sp & 255u) == 0u) { if (xb_ld(&(bar)[XB_TMO])) break; if (_sp > XB_SPIN_CAP) { atomicAdd(&(bar)[XB_TMO], 1u); break; } } } } while (0)
; __device__ __forceinline__ void xcd_barrier(const XcdBarrier& b) {
;     ...
;             XB_SPIN(xb_ld(&bar[XB_XGEN(b.x)]) == gen, bar);
;             __builtin_amdgcn_fence(__ATOMIC_ACQUIRE, "agent");
;             asm volatile("s_waitcnt vmcnt(0)" ::: "memory");
.LBB0_472:
	s_or_b64 exec, exec, s[10:11]
	s_waitcnt vmcnt(0)
	s_waitcnt vmcnt(0)

; __device__ __forceinline__ unsigned xb_ld(unsigned* p)              { return __hip_atomic_load(p, __ATOMIC_RELAXED, __HIP_MEMORY_SCOPE_AGENT); }
; __device__ __forceinline__ unsigned xb_add(unsigned* p, unsigned v) { return __hip_atomic_fetch_add(p, v, __ATOMIC_RELAXED, __HIP_MEMORY_SCOPE_AGENT); }
; #define XB_SPIN(cond, bar) do { unsigned _sp = 0; while (cond) { __builtin_amdgcn_s_sleep(1); \
;     if ((++_sp & 255u) == 0u) { if (xb_ld(&(bar)[XB_TMO])) break; if (_sp > XB_SPIN_CAP) { atomicAdd(&(bar)[XB_TMO], 1u); break; } } } } while (0)
; __device__ __forceinline__ void xcd_barrier(const XcdBarrier& b) {
;     ...
;         if (old + 1u == (gen + 1u) * nloc) {
;             __builtin_amdgcn_fence(__ATOMIC_RELEASE, "agent");
;             asm volatile("s_waitcnt vmcnt(0)" ::: "memory");
;             const unsigned og = xb_add(&bar[XB_TOP], 1u);
;             const unsigned tg = og / nx;
;             if (og + 1u == (tg + 1u) * nx) xb_add(&bar[XB_TOPGEN], 1u);
;             else XB_SPIN(xb_ld(&bar[XB_TOPGEN]) == tg, bar);
.LBB0_476:
	s_or_b64 exec, exec, s[10:11]
	buffer_inv sc1
	v_cvt_f32_u32_e32 v3, v0
	s_waitcnt vmcnt(0)
	v_readfirstlane_b32 s8, v2
	s_add_u32 s10, s62, 0x1de03500
	s_addc_u32 s11, s63, 0
	v_rcp_iflag_f32_e32 v3, v3
	v_add_u32_e32 v1, s8, v1
	v_add_u32_e32 v4, 1, v1
	s_mov_b64 s[12:13], -1
	v_mul_f32_e32 v2, 0x4f7ffffe, v3
	v_cvt_u32_f32_e32 v2, v2
	v_sub_u32_e32 v3, 0, v0
	v_mul_lo_u32 v3, v3, v2
	v_mul_hi_u32 v3, v2, v3
	v_add_u32_e32 v2, v2, v3
	v_mul_hi_u32 v2, v1, v2
	v_mul_lo_u32 v3, v2, v0
	v_sub_u32_e32 v1, v1, v3
	v_add_u32_e32 v5, 1, v2
	v_cmp_ge_u32_e32 vcc, v1, v0
	v_sub_u32_e32 v3, v1, v0
	s_nop 0
	v_cndmask_b32_e32 v2, v2, v5, vcc
	v_cndmask_b32_e32 v1, v1, v3, vcc
	v_add_u32_e32 v3, 1, v2
	v_cmp_ge_u32_e32 vcc, v1, v0
	s_nop 1
	v_cndmask_b32_e32 v2, v2, v3, vcc
	v_mul_lo_u32 v1, v0, v2
	v_add_u32_e32 v0, v1, v0
	v_cmp_ne_u32_e32 vcc, v4, v0
	v_mov_b64_e32 v[0:1], s[10:11]
	s_and_saveexec_b64 s[8:9], vcc
	s_cbranch_execz .LBB0_488
	v_mov_b32_e32 v0, 0
	global_load_dword v1, v0, s[10:11] sc1
	s_mov_b64 s[16:17], 0
	s_waitcnt vmcnt(0)
	v_cmp_eq_u32_e32 vcc, v1, v2
	s_and_saveexec_b64 s[14:15], vcc
	s_cbranch_execz .LBB0_487
	s_add_u32 s12, s62, 0x1de00200
	s_addc_u32 s13, s63, 0
	s_mov_b32 s26, 1
	s_branch .LBB0_480

; __device__ __forceinline__ unsigned xb_add(unsigned* p, unsigned v) { return __hip_atomic_fetch_add(p, v, __ATOMIC_RELAXED, __HIP_MEMORY_SCOPE_AGENT); }
; __device__ __forceinline__ void xcd_barrier(const XcdBarrier& b) {
;     ...
;             __builtin_amdgcn_fence(__ATOMIC_ACQUIRE, "agent");
;             xb_add(&bar[XB_XGEN(b.x)], 1u);
;             asm volatile("s_waitcnt vmcnt(0)" ::: "memory");
.LBB0_490:
	s_or_b64 exec, exec, s[8:9]
	s_mov_b64 s[8:9], exec
	v_mbcnt_lo_u32_b32 v0, s8, 0
	v_mbcnt_hi_u32_b32 v0, s9, v0
	v_cmp_eq_u32_e32 vcc, 0, v0
	s_waitcnt vmcnt(0)
	s_and_saveexec_b64 s[10:11], vcc
	s_cbranch_execz .LBB0_492
	s_bcnt1_i32_b64 s8, s[8:9]
	v_mov_b32_e32 v0, 0x2000
	v_mov_b32_e32 v1, s8
	global_atomic_add v0, v1, s[6:7] offset:1024
